# gather head butterfly: v_permlane16_swap + bank-masked DPP adds instead of 11 ds_bpermute round trips and 14 selects
# speedup vs baseline: 1.0071x; 1.0071x over previous
.LBB0_330:
	s_waitcnt vmcnt(22)
	v_cvt_scalef32_pk32_f32_fp6 v[0:31], v[32:37], 1.0
	v_pk_fma_f32 v[0:1], v[0:1], v[152:153], 0 op_sel_hi:[1,1,0]
	v_pk_fma_f32 v[2:3], v[2:3], v[170:171], 0 op_sel_hi:[1,1,0]
	v_pk_fma_f32 v[0:1], v[4:5], v[148:149], v[0:1]
	v_pk_fma_f32 v[2:3], v[6:7], v[172:173], v[2:3]
	v_pk_fma_f32 v[0:1], v[8:9], v[144:145], v[0:1]
	v_pk_fma_f32 v[2:3], v[10:11], v[174:175], v[2:3]
	v_pk_fma_f32 v[0:1], v[12:13], v[140:141], v[0:1]
	v_pk_fma_f32 v[2:3], v[14:15], v[178:179], v[2:3]
	v_pk_fma_f32 v[0:1], v[16:17], v[168:169], v[0:1]
	v_pk_fma_f32 v[2:3], v[18:19], v[180:181], v[2:3]
	v_pk_fma_f32 v[0:1], v[20:21], v[164:165], v[0:1]
	v_pk_fma_f32 v[2:3], v[22:23], v[182:183], v[2:3]
	v_pk_fma_f32 v[0:1], v[24:25], v[160:161], v[0:1]
	v_pk_fma_f32 v[2:3], v[26:27], v[184:185], v[2:3]
	v_pk_fma_f32 v[0:1], v[28:29], v[156:157], v[0:1]
	v_pk_fma_f32 v[2:3], v[30:31], v[186:187], v[2:3]
	v_add_f32_e32 v4, v2, v3
	v_add_f32_e32 v5, v0, v1
	v_add_f32_e32 v117, v4, v5
	s_waitcnt vmcnt(20)
	v_cvt_scalef32_pk32_f32_fp6 v[0:31], v[38:43], 1.0
	v_pk_fma_f32 v[0:1], v[0:1], v[152:153], 0 op_sel_hi:[1,1,0]
	v_pk_fma_f32 v[2:3], v[2:3], v[170:171], 0 op_sel_hi:[1,1,0]
	v_pk_fma_f32 v[0:1], v[4:5], v[148:149], v[0:1]
	v_pk_fma_f32 v[2:3], v[6:7], v[172:173], v[2:3]
	v_pk_fma_f32 v[0:1], v[8:9], v[144:145], v[0:1]
	v_pk_fma_f32 v[2:3], v[10:11], v[174:175], v[2:3]
	v_pk_fma_f32 v[0:1], v[12:13], v[140:141], v[0:1]
	v_pk_fma_f32 v[2:3], v[14:15], v[178:179], v[2:3]
	v_pk_fma_f32 v[0:1], v[16:17], v[168:169], v[0:1]
	v_pk_fma_f32 v[2:3], v[18:19], v[180:181], v[2:3]
	v_pk_fma_f32 v[0:1], v[20:21], v[164:165], v[0:1]
	v_pk_fma_f32 v[2:3], v[22:23], v[182:183], v[2:3]
	v_pk_fma_f32 v[0:1], v[24:25], v[160:161], v[0:1]
	v_pk_fma_f32 v[2:3], v[26:27], v[184:185], v[2:3]
	v_pk_fma_f32 v[0:1], v[28:29], v[156:157], v[0:1]
	v_pk_fma_f32 v[2:3], v[30:31], v[186:187], v[2:3]
	v_add_f32_e32 v4, v2, v3
	v_add_f32_e32 v5, v0, v1
	v_add_f32_e32 v131, v4, v5
	s_waitcnt vmcnt(18)
	v_cvt_scalef32_pk32_f32_fp6 v[0:31], v[44:49], 1.0
	v_pk_fma_f32 v[0:1], v[0:1], v[152:153], 0 op_sel_hi:[1,1,0]
	v_pk_fma_f32 v[2:3], v[2:3], v[170:171], 0 op_sel_hi:[1,1,0]
	v_pk_fma_f32 v[0:1], v[4:5], v[148:149], v[0:1]
	v_pk_fma_f32 v[2:3], v[6:7], v[172:173], v[2:3]
	v_pk_fma_f32 v[0:1], v[8:9], v[144:145], v[0:1]
	v_pk_fma_f32 v[2:3], v[10:11], v[174:175], v[2:3]
	v_pk_fma_f32 v[0:1], v[12:13], v[140:141], v[0:1]
	v_pk_fma_f32 v[2:3], v[14:15], v[178:179], v[2:3]
	v_pk_fma_f32 v[0:1], v[16:17], v[168:169], v[0:1]
	v_pk_fma_f32 v[2:3], v[18:19], v[180:181], v[2:3]
	v_pk_fma_f32 v[0:1], v[20:21], v[164:165], v[0:1]
	v_pk_fma_f32 v[2:3], v[22:23], v[182:183], v[2:3]
	v_pk_fma_f32 v[0:1], v[24:25], v[160:161], v[0:1]
	v_pk_fma_f32 v[2:3], v[26:27], v[184:185], v[2:3]
	v_pk_fma_f32 v[0:1], v[28:29], v[156:157], v[0:1]
	v_pk_fma_f32 v[2:3], v[30:31], v[186:187], v[2:3]
	v_add_f32_e32 v4, v2, v3
	v_add_f32_e32 v5, v0, v1
	v_add_f32_e32 v133, v4, v5
	s_waitcnt vmcnt(16)
	v_cvt_scalef32_pk32_f32_fp6 v[0:31], v[50:55], 1.0
	v_pk_fma_f32 v[0:1], v[0:1], v[152:153], 0 op_sel_hi:[1,1,0]
	v_pk_fma_f32 v[2:3], v[2:3], v[170:171], 0 op_sel_hi:[1,1,0]
	v_pk_fma_f32 v[0:1], v[4:5], v[148:149], v[0:1]
	v_pk_fma_f32 v[2:3], v[6:7], v[172:173], v[2:3]
	v_pk_fma_f32 v[0:1], v[8:9], v[144:145], v[0:1]
	v_pk_fma_f32 v[2:3], v[10:11], v[174:175], v[2:3]
	v_pk_fma_f32 v[0:1], v[12:13], v[140:141], v[0:1]
	v_pk_fma_f32 v[2:3], v[14:15], v[178:179], v[2:3]
	v_pk_fma_f32 v[0:1], v[16:17], v[168:169], v[0:1]
	v_pk_fma_f32 v[2:3], v[18:19], v[180:181], v[2:3]
	v_pk_fma_f32 v[0:1], v[20:21], v[164:165], v[0:1]
	v_pk_fma_f32 v[2:3], v[22:23], v[182:183], v[2:3]
	v_pk_fma_f32 v[0:1], v[24:25], v[160:161], v[0:1]
	v_pk_fma_f32 v[2:3], v[26:27], v[184:185], v[2:3]
	v_pk_fma_f32 v[0:1], v[28:29], v[156:157], v[0:1]
	v_pk_fma_f32 v[2:3], v[30:31], v[186:187], v[2:3]
	v_add_f32_e32 v4, v2, v3
	v_add_f32_e32 v5, v0, v1
	v_add_f32_e32 v218, v4, v5
	s_waitcnt vmcnt(14)
	v_cvt_scalef32_pk32_f32_fp6 v[0:31], v[56:61], 1.0
	v_pk_fma_f32 v[0:1], v[0:1], v[152:153], 0 op_sel_hi:[1,1,0]
	v_pk_fma_f32 v[2:3], v[2:3], v[170:171], 0 op_sel_hi:[1,1,0]
	v_pk_fma_f32 v[0:1], v[4:5], v[148:149], v[0:1]
	v_pk_fma_f32 v[2:3], v[6:7], v[172:173], v[2:3]
	v_pk_fma_f32 v[0:1], v[8:9], v[144:145], v[0:1]
	v_pk_fma_f32 v[2:3], v[10:11], v[174:175], v[2:3]
	v_pk_fma_f32 v[0:1], v[12:13], v[140:141], v[0:1]
	v_pk_fma_f32 v[2:3], v[14:15], v[178:179], v[2:3]
	v_pk_fma_f32 v[0:1], v[16:17], v[168:169], v[0:1]
	v_pk_fma_f32 v[2:3], v[18:19], v[180:181], v[2:3]
	v_pk_fma_f32 v[0:1], v[20:21], v[164:165], v[0:1]
	v_pk_fma_f32 v[2:3], v[22:23], v[182:183], v[2:3]
	v_pk_fma_f32 v[0:1], v[24:25], v[160:161], v[0:1]
	v_pk_fma_f32 v[2:3], v[26:27], v[184:185], v[2:3]
	v_pk_fma_f32 v[0:1], v[28:29], v[156:157], v[0:1]
	v_pk_fma_f32 v[2:3], v[30:31], v[186:187], v[2:3]
	v_add_f32_e32 v4, v2, v3
	v_add_f32_e32 v5, v0, v1
	v_add_f32_e32 v219, v4, v5
	s_waitcnt vmcnt(12)
	v_cvt_scalef32_pk32_f32_fp6 v[0:31], v[62:67], 1.0
	v_pk_fma_f32 v[0:1], v[0:1], v[152:153], 0 op_sel_hi:[1,1,0]
	v_pk_fma_f32 v[2:3], v[2:3], v[170:171], 0 op_sel_hi:[1,1,0]
	v_pk_fma_f32 v[0:1], v[4:5], v[148:149], v[0:1]
	v_pk_fma_f32 v[2:3], v[6:7], v[172:173], v[2:3]
	v_pk_fma_f32 v[0:1], v[8:9], v[144:145], v[0:1]
	v_pk_fma_f32 v[2:3], v[10:11], v[174:175], v[2:3]
	v_pk_fma_f32 v[0:1], v[12:13], v[140:141], v[0:1]
	v_pk_fma_f32 v[2:3], v[14:15], v[178:179], v[2:3]
	v_pk_fma_f32 v[0:1], v[16:17], v[168:169], v[0:1]
	v_pk_fma_f32 v[2:3], v[18:19], v[180:181], v[2:3]
	v_pk_fma_f32 v[0:1], v[20:21], v[164:165], v[0:1]
	v_pk_fma_f32 v[2:3], v[22:23], v[182:183], v[2:3]
	v_pk_fma_f32 v[0:1], v[24:25], v[160:161], v[0:1]
	v_pk_fma_f32 v[2:3], v[26:27], v[184:185], v[2:3]
	v_pk_fma_f32 v[0:1], v[28:29], v[156:157], v[0:1]
	v_pk_fma_f32 v[2:3], v[30:31], v[186:187], v[2:3]
	v_add_f32_e32 v4, v2, v3
	v_add_f32_e32 v5, v0, v1
	v_add_f32_e32 v246, v4, v5
	s_waitcnt vmcnt(10)
	v_cvt_scalef32_pk32_f32_fp6 v[0:31], v[68:73], 1.0
	v_pk_fma_f32 v[0:1], v[0:1], v[152:153], 0 op_sel_hi:[1,1,0]
	v_pk_fma_f32 v[2:3], v[2:3], v[170:171], 0 op_sel_hi:[1,1,0]
	v_pk_fma_f32 v[0:1], v[4:5], v[148:149], v[0:1]
	v_pk_fma_f32 v[2:3], v[6:7], v[172:173], v[2:3]
	v_pk_fma_f32 v[0:1], v[8:9], v[144:145], v[0:1]
	v_pk_fma_f32 v[2:3], v[10:11], v[174:175], v[2:3]
	v_pk_fma_f32 v[0:1], v[12:13], v[140:141], v[0:1]
	v_pk_fma_f32 v[2:3], v[14:15], v[178:179], v[2:3]
	v_pk_fma_f32 v[0:1], v[16:17], v[168:169], v[0:1]
	v_pk_fma_f32 v[2:3], v[18:19], v[180:181], v[2:3]
	v_pk_fma_f32 v[0:1], v[20:21], v[164:165], v[0:1]
	v_pk_fma_f32 v[2:3], v[22:23], v[182:183], v[2:3]
	v_pk_fma_f32 v[0:1], v[24:25], v[160:161], v[0:1]
	v_pk_fma_f32 v[2:3], v[26:27], v[184:185], v[2:3]
	v_pk_fma_f32 v[0:1], v[28:29], v[156:157], v[0:1]
	v_pk_fma_f32 v[2:3], v[30:31], v[186:187], v[2:3]
	v_add_f32_e32 v4, v2, v3
	v_add_f32_e32 v5, v0, v1
	v_add_f32_e32 v247, v4, v5
	s_waitcnt vmcnt(8)
	v_cvt_scalef32_pk32_f32_fp6 v[0:31], v[74:79], 1.0
	v_pk_fma_f32 v[0:1], v[0:1], v[152:153], 0 op_sel_hi:[1,1,0]
	v_pk_fma_f32 v[2:3], v[2:3], v[170:171], 0 op_sel_hi:[1,1,0]
	v_pk_fma_f32 v[0:1], v[4:5], v[148:149], v[0:1]
	v_pk_fma_f32 v[2:3], v[6:7], v[172:173], v[2:3]
	v_pk_fma_f32 v[0:1], v[8:9], v[144:145], v[0:1]
	v_pk_fma_f32 v[2:3], v[10:11], v[174:175], v[2:3]
	v_pk_fma_f32 v[0:1], v[12:13], v[140:141], v[0:1]
	v_pk_fma_f32 v[2:3], v[14:15], v[178:179], v[2:3]
	v_pk_fma_f32 v[0:1], v[16:17], v[168:169], v[0:1]
	v_pk_fma_f32 v[2:3], v[18:19], v[180:181], v[2:3]
	v_pk_fma_f32 v[0:1], v[20:21], v[164:165], v[0:1]
	v_pk_fma_f32 v[2:3], v[22:23], v[182:183], v[2:3]
	v_pk_fma_f32 v[0:1], v[24:25], v[160:161], v[0:1]
	v_pk_fma_f32 v[2:3], v[26:27], v[184:185], v[2:3]
	v_pk_fma_f32 v[0:1], v[28:29], v[156:157], v[0:1]
	v_pk_fma_f32 v[2:3], v[30:31], v[186:187], v[2:3]
	v_add_f32_e32 v4, v2, v3
	v_add_f32_e32 v5, v0, v1
	v_add_f32_e32 v1, v4, v5
	v_add_u32_e32 v8, s24, v239
	ds_read_b32 v12, v8 offset:512
	s_waitcnt lgkmcnt(0)
	ds_bpermute_b32 v0, v255, v12
	ds_bpermute_b32 v2, v255, v12 offset:16
	ds_bpermute_b32 v3, v255, v12 offset:32
	ds_bpermute_b32 v6, v255, v12 offset:48
	ds_bpermute_b32 v7, v255, v12 offset:64
	ds_bpermute_b32 v10, v255, v12 offset:80
	ds_bpermute_b32 v11, v255, v12 offset:96
	ds_bpermute_b32 v14, v255, v12 offset:112
	s_waitcnt lgkmcnt(7)
	v_mad_i64_i32 v[22:23], s[2:3], v0, s28, v[118:119]
	global_load_dwordx2 v[36:37], v[22:23], off offset:16
	global_load_dwordx4 v[32:35], v[22:23], off
	s_waitcnt lgkmcnt(6)
	v_mad_i64_i32 v[24:25], s[2:3], v2, s28, v[118:119]
	global_load_dwordx2 v[42:43], v[24:25], off offset:16
	global_load_dwordx4 v[38:41], v[24:25], off
	s_waitcnt lgkmcnt(5)
	v_mad_i64_i32 v[22:23], s[2:3], v3, s28, v[118:119]
	global_load_dwordx2 v[48:49], v[22:23], off offset:16
	global_load_dwordx4 v[44:47], v[22:23], off
	s_waitcnt lgkmcnt(4)
	v_mad_i64_i32 v[24:25], s[2:3], v6, s28, v[118:119]
	global_load_dwordx2 v[54:55], v[24:25], off offset:16
	global_load_dwordx4 v[50:53], v[24:25], off
	s_waitcnt lgkmcnt(3)
	v_mad_i64_i32 v[22:23], s[2:3], v7, s28, v[118:119]
	global_load_dwordx2 v[60:61], v[22:23], off offset:16
	global_load_dwordx4 v[56:59], v[22:23], off
	s_waitcnt lgkmcnt(2)
	v_mad_i64_i32 v[24:25], s[2:3], v10, s28, v[118:119]
	global_load_dwordx2 v[66:67], v[24:25], off offset:16
	global_load_dwordx4 v[62:65], v[24:25], off
	s_waitcnt lgkmcnt(1)
	v_mad_i64_i32 v[22:23], s[2:3], v11, s28, v[118:119]
	global_load_dwordx2 v[72:73], v[22:23], off offset:16
	global_load_dwordx4 v[68:71], v[22:23], off
	s_waitcnt lgkmcnt(0)
	v_mad_i64_i32 v[24:25], s[2:3], v14, s28, v[118:119]
	global_load_dwordx2 v[78:79], v[24:25], off offset:16
	global_load_dwordx4 v[74:77], v[24:25], off
	ds_read_b64 v[16:17], v8
	s_nop 1
	v_permlane16_swap_b32_e32 v117, v219
	v_permlane16_swap_b32_e32 v131, v246
	v_permlane16_swap_b32_e32 v133, v247
	v_permlane16_swap_b32_e32 v218, v1
	v_add_f32_e32 v117, v117, v219
	v_add_f32_e32 v131, v131, v246
	v_add_f32_e32 v133, v133, v247
	v_add_f32_e32 v218, v218, v1
	s_nop 1
	v_add_f32_dpp v117, v117, v117 row_ror:8 row_mask:0xf bank_mask:0x3
	v_add_f32_dpp v117, v133, v133 row_ror:8 row_mask:0xf bank_mask:0xc
	v_add_f32_dpp v131, v131, v131 row_ror:8 row_mask:0xf bank_mask:0x3
	v_add_f32_dpp v131, v218, v218 row_ror:8 row_mask:0xf bank_mask:0xc
	s_nop 1
	v_add_f32_dpp v117, v117, v117 row_ror:12 row_mask:0xf bank_mask:0x5
	v_add_f32_dpp v117, v131, v131 row_ror:4 row_mask:0xf bank_mask:0xa
	s_nop 1
	v_add_f32_dpp v117, v117, v117 quad_perm:[2,3,0,1] row_mask:0xf bank_mask:0xf
	s_nop 1
	v_add_f32_dpp v1, v117, v117 quad_perm:[1,0,3,2] row_mask:0xf bank_mask:0xf
	s_waitcnt lgkmcnt(0)
	v_mul_f32_e32 v18, 0x3caaaaab, v1
	v_mul_f32_e32 v16, 0x3f3504f3, v18
	v_cmp_nlt_f32_e64 s[2:3], |v16|, 1.0
	s_and_saveexec_b64 s[26:27], s[2:3]
	s_xor_b64 s[2:3], exec, s[26:27]
	s_cbranch_execz .LBB0_332
	s_mov_b32 s25, 0x378e98ab
	v_fma_f32 v1, |v16|, s25, v233
	s_mov_b32 s25, 0x3b7cd369
	v_fma_f32 v1, |v16|, v1, s25
	s_mov_b32 s25, 0xbcc618b2
	v_fma_f32 v1, |v16|, v1, s25
	s_mov_b32 s25, 0x3dda74e4
	v_fma_f32 v1, |v16|, v1, s25
	s_mov_b32 s25, 0x3f228afd
	v_fma_f32 v1, |v16|, v1, s25
	s_mov_b32 s25, 0x3e03c728
	v_fma_f32 v1, |v16|, v1, s25
	v_fma_f32 v1, |v16|, v1, |v16|
	v_mul_f32_e32 v4, 0xbfb8aa3b, v1
	s_mov_b32 s25, 0xbfb8aa3b
	v_fma_f32 v5, v1, s25, -v4
	v_rndne_f32_e32 v8, v4
	v_fmac_f32_e32 v5, 0xb2a5705f, v1
	v_sub_f32_e32 v4, v4, v8
	v_add_f32_e32 v4, v4, v5
	v_cvt_i32_f32_e32 v5, v8
	v_exp_f32_e32 v4, v4
	s_mov_b32 s25, 0x42ce8ed0
	v_cmp_nlt_f32_e32 vcc, s25, v1
	s_mov_b32 s25, 0xc2b17218
	v_ldexp_f32 v4, v4, v5
	v_cndmask_b32_e32 v4, 0, v4, vcc
	v_cmp_ngt_f32_e32 vcc, s25, v1
	s_nop 1
	v_cndmask_b32_e32 v1, v234, v4, vcc
	v_sub_f32_e32 v19, 1.0, v1

.LBB0_334:
	s_waitcnt vmcnt(8)
	v_cvt_scalef32_pk32_f32_fp6 v[0:31], v[74:79], 1.0
	v_pk_fma_f32 v[2:3], v[2:3], v[170:171], 0 op_sel_hi:[1,1,0]
	v_pk_fma_f32 v[0:1], v[0:1], v[152:153], 0 op_sel_hi:[1,1,0]
	v_pk_fma_f32 v[2:3], v[6:7], v[172:173], v[2:3]
	v_pk_fma_f32 v[0:1], v[4:5], v[148:149], v[0:1]
	v_pk_fma_f32 v[2:3], v[10:11], v[174:175], v[2:3]
	v_pk_fma_f32 v[0:1], v[8:9], v[144:145], v[0:1]
	v_pk_fma_f32 v[2:3], v[14:15], v[178:179], v[2:3]
	v_pk_fma_f32 v[0:1], v[12:13], v[140:141], v[0:1]
	v_pk_fma_f32 v[2:3], v[18:19], v[180:181], v[2:3]
	v_pk_fma_f32 v[0:1], v[16:17], v[168:169], v[0:1]
	v_pk_fma_f32 v[2:3], v[22:23], v[182:183], v[2:3]
	v_pk_fma_f32 v[0:1], v[20:21], v[164:165], v[0:1]
	v_pk_fma_f32 v[2:3], v[26:27], v[184:185], v[2:3]
	v_pk_fma_f32 v[0:1], v[24:25], v[160:161], v[0:1]
	v_pk_fma_f32 v[2:3], v[30:31], v[186:187], v[2:3]
	v_pk_fma_f32 v[0:1], v[28:29], v[156:157], v[0:1]
	v_add_f32_e32 v4, v2, v3
	v_add_f32_e32 v5, v0, v1
	ds_read_b64 v[218:219], v239 offset:3584
	v_add_f32_e32 v74, v4, v5
	v_cvt_scalef32_pk32_f32_fp6 v[0:31], v[68:73], 1.0
	v_pk_fma_f32 v[2:3], v[2:3], v[170:171], 0 op_sel_hi:[1,1,0]
	v_pk_fma_f32 v[0:1], v[0:1], v[152:153], 0 op_sel_hi:[1,1,0]
	v_pk_fma_f32 v[2:3], v[6:7], v[172:173], v[2:3]
	v_pk_fma_f32 v[0:1], v[4:5], v[148:149], v[0:1]
	v_pk_fma_f32 v[2:3], v[10:11], v[174:175], v[2:3]
	v_pk_fma_f32 v[0:1], v[8:9], v[144:145], v[0:1]
	v_pk_fma_f32 v[2:3], v[14:15], v[178:179], v[2:3]
	v_pk_fma_f32 v[0:1], v[12:13], v[140:141], v[0:1]
	v_pk_fma_f32 v[2:3], v[18:19], v[180:181], v[2:3]
	v_pk_fma_f32 v[0:1], v[16:17], v[168:169], v[0:1]
	v_pk_fma_f32 v[2:3], v[22:23], v[182:183], v[2:3]
	v_pk_fma_f32 v[0:1], v[20:21], v[164:165], v[0:1]
	v_pk_fma_f32 v[2:3], v[26:27], v[184:185], v[2:3]
	v_pk_fma_f32 v[0:1], v[24:25], v[160:161], v[0:1]
	v_pk_fma_f32 v[2:3], v[30:31], v[186:187], v[2:3]
	v_pk_fma_f32 v[0:1], v[28:29], v[156:157], v[0:1]
	v_add_f32_e32 v4, v2, v3
	v_add_f32_e32 v5, v0, v1
	v_add_f32_e32 v68, v4, v5
	v_cvt_scalef32_pk32_f32_fp6 v[0:31], v[62:67], 1.0
	v_pk_fma_f32 v[2:3], v[2:3], v[170:171], 0 op_sel_hi:[1,1,0]
	v_pk_fma_f32 v[0:1], v[0:1], v[152:153], 0 op_sel_hi:[1,1,0]
	v_pk_fma_f32 v[2:3], v[6:7], v[172:173], v[2:3]
	v_pk_fma_f32 v[0:1], v[4:5], v[148:149], v[0:1]
	v_pk_fma_f32 v[2:3], v[10:11], v[174:175], v[2:3]
	v_pk_fma_f32 v[0:1], v[8:9], v[144:145], v[0:1]
	v_pk_fma_f32 v[2:3], v[14:15], v[178:179], v[2:3]
	v_pk_fma_f32 v[0:1], v[12:13], v[140:141], v[0:1]
	v_pk_fma_f32 v[2:3], v[18:19], v[180:181], v[2:3]
	v_pk_fma_f32 v[0:1], v[16:17], v[168:169], v[0:1]
	v_pk_fma_f32 v[2:3], v[22:23], v[182:183], v[2:3]
	v_pk_fma_f32 v[0:1], v[20:21], v[164:165], v[0:1]
	v_pk_fma_f32 v[2:3], v[26:27], v[184:185], v[2:3]
	v_pk_fma_f32 v[0:1], v[24:25], v[160:161], v[0:1]
	v_pk_fma_f32 v[2:3], v[30:31], v[186:187], v[2:3]
	v_pk_fma_f32 v[0:1], v[28:29], v[156:157], v[0:1]
	v_add_f32_e32 v4, v2, v3
	v_add_f32_e32 v5, v0, v1
	v_add_f32_e32 v62, v4, v5
	v_cvt_scalef32_pk32_f32_fp6 v[0:31], v[56:61], 1.0
	v_pk_fma_f32 v[2:3], v[2:3], v[170:171], 0 op_sel_hi:[1,1,0]
	v_pk_fma_f32 v[0:1], v[0:1], v[152:153], 0 op_sel_hi:[1,1,0]
	v_pk_fma_f32 v[2:3], v[6:7], v[172:173], v[2:3]
	v_pk_fma_f32 v[0:1], v[4:5], v[148:149], v[0:1]
	v_pk_fma_f32 v[2:3], v[10:11], v[174:175], v[2:3]
	v_pk_fma_f32 v[0:1], v[8:9], v[144:145], v[0:1]
	v_pk_fma_f32 v[2:3], v[14:15], v[178:179], v[2:3]
	v_pk_fma_f32 v[0:1], v[12:13], v[140:141], v[0:1]
	v_pk_fma_f32 v[2:3], v[18:19], v[180:181], v[2:3]
	v_pk_fma_f32 v[0:1], v[16:17], v[168:169], v[0:1]
	v_pk_fma_f32 v[2:3], v[22:23], v[182:183], v[2:3]
	v_pk_fma_f32 v[0:1], v[20:21], v[164:165], v[0:1]
	v_pk_fma_f32 v[2:3], v[26:27], v[184:185], v[2:3]
	v_pk_fma_f32 v[0:1], v[24:25], v[160:161], v[0:1]
	v_pk_fma_f32 v[2:3], v[30:31], v[186:187], v[2:3]
	v_pk_fma_f32 v[0:1], v[28:29], v[156:157], v[0:1]
	v_add_f32_e32 v4, v2, v3
	v_add_f32_e32 v5, v0, v1
	v_add_f32_e32 v56, v4, v5
	v_cvt_scalef32_pk32_f32_fp6 v[0:31], v[50:55], 1.0
	v_pk_fma_f32 v[2:3], v[2:3], v[170:171], 0 op_sel_hi:[1,1,0]
	v_pk_fma_f32 v[0:1], v[0:1], v[152:153], 0 op_sel_hi:[1,1,0]
	v_pk_fma_f32 v[2:3], v[6:7], v[172:173], v[2:3]
	v_pk_fma_f32 v[0:1], v[4:5], v[148:149], v[0:1]
	v_pk_fma_f32 v[2:3], v[10:11], v[174:175], v[2:3]
	v_pk_fma_f32 v[0:1], v[8:9], v[144:145], v[0:1]
	v_pk_fma_f32 v[2:3], v[14:15], v[178:179], v[2:3]
	v_pk_fma_f32 v[0:1], v[12:13], v[140:141], v[0:1]
	v_pk_fma_f32 v[2:3], v[18:19], v[180:181], v[2:3]
	v_pk_fma_f32 v[0:1], v[16:17], v[168:169], v[0:1]
	v_pk_fma_f32 v[2:3], v[22:23], v[182:183], v[2:3]
	v_pk_fma_f32 v[0:1], v[20:21], v[164:165], v[0:1]
	v_pk_fma_f32 v[2:3], v[26:27], v[184:185], v[2:3]
	v_pk_fma_f32 v[0:1], v[24:25], v[160:161], v[0:1]
	v_pk_fma_f32 v[2:3], v[30:31], v[186:187], v[2:3]
	v_pk_fma_f32 v[0:1], v[28:29], v[156:157], v[0:1]
	v_add_f32_e32 v4, v2, v3
	v_add_f32_e32 v5, v0, v1
	v_add_f32_e32 v50, v4, v5
	v_cvt_scalef32_pk32_f32_fp6 v[0:31], v[44:49], 1.0
	v_pk_fma_f32 v[2:3], v[2:3], v[170:171], 0 op_sel_hi:[1,1,0]
	v_pk_fma_f32 v[0:1], v[0:1], v[152:153], 0 op_sel_hi:[1,1,0]
	v_pk_fma_f32 v[2:3], v[6:7], v[172:173], v[2:3]
	v_pk_fma_f32 v[0:1], v[4:5], v[148:149], v[0:1]
	v_pk_fma_f32 v[2:3], v[10:11], v[174:175], v[2:3]
	v_pk_fma_f32 v[0:1], v[8:9], v[144:145], v[0:1]
	v_pk_fma_f32 v[2:3], v[14:15], v[178:179], v[2:3]
	v_pk_fma_f32 v[0:1], v[12:13], v[140:141], v[0:1]
	v_pk_fma_f32 v[2:3], v[18:19], v[180:181], v[2:3]
	v_pk_fma_f32 v[0:1], v[16:17], v[168:169], v[0:1]
	v_pk_fma_f32 v[2:3], v[22:23], v[182:183], v[2:3]
	v_pk_fma_f32 v[0:1], v[20:21], v[164:165], v[0:1]
	v_pk_fma_f32 v[2:3], v[26:27], v[184:185], v[2:3]
	v_pk_fma_f32 v[0:1], v[24:25], v[160:161], v[0:1]
	v_pk_fma_f32 v[2:3], v[30:31], v[186:187], v[2:3]
	v_pk_fma_f32 v[0:1], v[28:29], v[156:157], v[0:1]
	v_add_f32_e32 v4, v2, v3
	v_add_f32_e32 v5, v0, v1
	v_add_f32_e32 v44, v4, v5
	v_cvt_scalef32_pk32_f32_fp6 v[0:31], v[38:43], 1.0
	v_pk_fma_f32 v[2:3], v[2:3], v[170:171], 0 op_sel_hi:[1,1,0]
	v_pk_fma_f32 v[0:1], v[0:1], v[152:153], 0 op_sel_hi:[1,1,0]
	v_pk_fma_f32 v[2:3], v[6:7], v[172:173], v[2:3]
	v_pk_fma_f32 v[0:1], v[4:5], v[148:149], v[0:1]
	v_pk_fma_f32 v[2:3], v[10:11], v[174:175], v[2:3]
	v_pk_fma_f32 v[0:1], v[8:9], v[144:145], v[0:1]
	v_pk_fma_f32 v[2:3], v[14:15], v[178:179], v[2:3]
	v_pk_fma_f32 v[0:1], v[12:13], v[140:141], v[0:1]
	v_pk_fma_f32 v[2:3], v[18:19], v[180:181], v[2:3]
	v_pk_fma_f32 v[0:1], v[16:17], v[168:169], v[0:1]
	v_pk_fma_f32 v[2:3], v[22:23], v[182:183], v[2:3]
	v_pk_fma_f32 v[0:1], v[20:21], v[164:165], v[0:1]
	v_pk_fma_f32 v[2:3], v[26:27], v[184:185], v[2:3]
	v_pk_fma_f32 v[0:1], v[24:25], v[160:161], v[0:1]
	v_pk_fma_f32 v[2:3], v[30:31], v[186:187], v[2:3]
	v_pk_fma_f32 v[0:1], v[28:29], v[156:157], v[0:1]
	v_add_f32_e32 v4, v2, v3
	v_add_f32_e32 v5, v0, v1
	v_add_f32_e32 v38, v4, v5
	v_cvt_scalef32_pk32_f32_fp6 v[0:31], v[32:37], 1.0
	v_pk_fma_f32 v[2:3], v[2:3], v[170:171], 0 op_sel_hi:[1,1,0]
	v_pk_fma_f32 v[0:1], v[0:1], v[152:153], 0 op_sel_hi:[1,1,0]
	v_pk_fma_f32 v[2:3], v[6:7], v[172:173], v[2:3]
	v_pk_fma_f32 v[0:1], v[4:5], v[148:149], v[0:1]
	v_pk_fma_f32 v[2:3], v[10:11], v[174:175], v[2:3]
	v_pk_fma_f32 v[0:1], v[8:9], v[144:145], v[0:1]
	v_pk_fma_f32 v[2:3], v[14:15], v[178:179], v[2:3]
	v_pk_fma_f32 v[0:1], v[12:13], v[140:141], v[0:1]
	v_pk_fma_f32 v[2:3], v[18:19], v[180:181], v[2:3]
	v_pk_fma_f32 v[0:1], v[16:17], v[168:169], v[0:1]
	v_pk_fma_f32 v[2:3], v[22:23], v[182:183], v[2:3]
	v_pk_fma_f32 v[0:1], v[20:21], v[164:165], v[0:1]
	v_pk_fma_f32 v[2:3], v[26:27], v[184:185], v[2:3]
	v_pk_fma_f32 v[0:1], v[24:25], v[160:161], v[0:1]
	v_pk_fma_f32 v[2:3], v[30:31], v[186:187], v[2:3]
	v_pk_fma_f32 v[0:1], v[28:29], v[156:157], v[0:1]
	v_add_f32_e32 v4, v2, v3
	v_add_f32_e32 v5, v0, v1
	v_add_f32_e32 v0, v4, v5
	s_nop 1
	v_permlane16_swap_b32_e32 v0, v56
	v_permlane16_swap_b32_e32 v38, v62
	v_permlane16_swap_b32_e32 v44, v68
	v_permlane16_swap_b32_e32 v50, v74
	v_add_f32_e32 v0, v0, v56
	v_add_f32_e32 v38, v38, v62
	v_add_f32_e32 v44, v44, v68
	v_add_f32_e32 v50, v50, v74
	s_nop 1
	v_add_f32_dpp v0, v0, v0 row_ror:8 row_mask:0xf bank_mask:0x3
	v_add_f32_dpp v0, v44, v44 row_ror:8 row_mask:0xf bank_mask:0xc
	v_add_f32_dpp v38, v38, v38 row_ror:8 row_mask:0xf bank_mask:0x3
	v_add_f32_dpp v38, v50, v50 row_ror:8 row_mask:0xf bank_mask:0xc
	s_nop 1
	v_add_f32_dpp v0, v0, v0 row_ror:12 row_mask:0xf bank_mask:0x5
	v_add_f32_dpp v0, v38, v38 row_ror:4 row_mask:0xf bank_mask:0xa
	s_nop 1
	v_add_f32_dpp v0, v0, v0 quad_perm:[2,3,0,1] row_mask:0xf bank_mask:0xf
	s_nop 1
	v_add_f32_dpp v0, v0, v0 quad_perm:[1,0,3,2] row_mask:0xf bank_mask:0xf
	s_waitcnt lgkmcnt(0)
	v_mul_f32_e32 v1, 0x3caaaaab, v0
	v_mul_f32_e32 v0, 0x3f3504f3, v1
	v_cmp_nlt_f32_e64 s[2:3], |v0|, 1.0
	s_and_saveexec_b64 s[24:25], s[2:3]
	s_xor_b64 s[2:3], exec, s[24:25]
	s_cbranch_execz .LBB0_336
	s_mov_b32 s24, 0x378e98ab
	v_fma_f32 v2, |v0|, s24, v233
	s_mov_b32 s24, 0x3b7cd369
	v_fma_f32 v2, |v0|, v2, s24
	s_mov_b32 s24, 0xbcc618b2
	v_fma_f32 v2, |v0|, v2, s24
	s_mov_b32 s24, 0x3dda74e4
	v_fma_f32 v2, |v0|, v2, s24
	s_mov_b32 s24, 0x3f228afd
	v_fma_f32 v2, |v0|, v2, s24
	s_mov_b32 s24, 0x3e03c728
	v_fma_f32 v2, |v0|, v2, s24
	v_fma_f32 v2, |v0|, v2, |v0|
	v_mul_f32_e32 v3, 0xbfb8aa3b, v2
	s_mov_b32 s24, 0xbfb8aa3b
	v_fma_f32 v4, v2, s24, -v3
	v_rndne_f32_e32 v5, v3
	v_fmac_f32_e32 v4, 0xb2a5705f, v2
	v_sub_f32_e32 v3, v3, v5
	v_add_f32_e32 v3, v3, v4
	v_cvt_i32_f32_e32 v4, v5
	v_exp_f32_e32 v3, v3
	s_mov_b32 s24, 0x42ce8ed0
	v_cmp_nlt_f32_e32 vcc, s24, v2
	s_mov_b32 s24, 0xc2b17218
	v_ldexp_f32 v3, v3, v4
	v_cndmask_b32_e32 v3, 0, v3, vcc
	v_cmp_ngt_f32_e32 vcc, s24, v2
	s_nop 1
	v_cndmask_b32_e32 v2, v234, v3, vcc
	v_sub_f32_e32 v2, 1.0, v2
